# mix preamble rewritten: coefficient loads and 2x16 adaLN partial loads issued as overlapped bursts behind counted vmcnt waits (was 13 dependent round trips)
# speedup vs baseline: 1.0110x; 1.0004x over previous
.LBB0_119:
	s_or_b64 exec, exec, s[4:5]
	s_waitcnt lgkmcnt(0)
	s_barrier
	s_load_dwordx2 s[0:1], s[46:47], 0x120
	s_load_dwordx2 s[6:7], s[46:47], 0x0
	s_load_dwordx2 s[8:9], s[46:47], 0x20
	s_load_dwordx2 s[10:11], s[46:47], 0x40
	v_mov_b32_e32 v12, v214
	s_waitcnt lgkmcnt(0)
	v_mov_b32_e32 v0, s1
	v_mov_b32_e32 v1, s0
	s_movk_i32 s0, 0x1000
	s_nop 0
	v_readfirstlane_b32 s4, v1
	v_readfirstlane_b32 s5, v0
	v_cmp_gt_i32_e32 vcc, s0, v12
	v_lshlrev_b32_e32 v4, 2, v12
	v_lshlrev_b32_e32 v244, 4, v12
	s_mov_b64 s[12:13], s[10:11]
	global_load_dwordx4 v[140:143], v244, s[12:13]
	s_add_u32 s12, s12, 0x2000
	s_addc_u32 s13, s13, 0
	global_load_dwordx4 v[144:147], v244, s[12:13]
	s_add_u32 s12, s12, 0x2000
	s_addc_u32 s13, s13, 0
	global_load_dwordx4 v[148:151], v244, s[12:13]
	s_add_u32 s12, s12, 0x2000
	s_addc_u32 s13, s13, 0
	global_load_dwordx4 v[152:155], v244, s[12:13]
	s_add_u32 s12, s12, 0x2000
	s_addc_u32 s13, s13, 0
	global_load_dwordx4 v[156:159], v244, s[12:13]
	s_add_u32 s12, s12, 0x2000
	s_addc_u32 s13, s13, 0
	global_load_dwordx4 v[160:163], v244, s[12:13]
	global_load_dwordx4 v[164:167], v244, s[8:9]
	s_lshr_b32 s0, s2, 6
	s_lshl_b32 s0, s0, 14
	v_add_u32_e32 v245, s0, v244
	v_add_u32_e32 v246, 0x2000, v245
	v_add_u32_e32 v247, 0x10000, v244
	s_add_u32 s14, s4, 0xde80000
	s_addc_u32 s15, s5, 0
	s_mov_b64 s[16:17], s[14:15]
	global_load_dwordx4 v[168:171], v245, s[14:15]
	s_add_u32 s14, s14, 0x10000
	s_addc_u32 s15, s15, 0
	global_load_dwordx4 v[172:175], v245, s[14:15]
	s_add_u32 s14, s14, 0x10000
	s_addc_u32 s15, s15, 0
	global_load_dwordx4 v[176:179], v245, s[14:15]
	s_add_u32 s14, s14, 0x10000
	s_addc_u32 s15, s15, 0
	global_load_dwordx4 v[180:183], v245, s[14:15]
	s_add_u32 s14, s14, 0x10000
	s_addc_u32 s15, s15, 0
	global_load_dwordx4 v[184:187], v245, s[14:15]
	s_add_u32 s14, s14, 0x10000
	s_addc_u32 s15, s15, 0
	global_load_dwordx4 v[188:191], v245, s[14:15]
	s_add_u32 s14, s14, 0x10000
	s_addc_u32 s15, s15, 0
	global_load_dwordx4 v[192:195], v245, s[14:15]
	s_add_u32 s14, s14, 0x10000
	s_addc_u32 s15, s15, 0
	global_load_dwordx4 v[196:199], v245, s[14:15]
	s_add_u32 s14, s14, 0x10000
	s_addc_u32 s15, s15, 0
	global_load_dwordx4 v[200:203], v245, s[14:15]
	s_add_u32 s14, s14, 0x10000
	s_addc_u32 s15, s15, 0
	global_load_dwordx4 v[204:207], v245, s[14:15]
	s_add_u32 s14, s14, 0x10000
	s_addc_u32 s15, s15, 0
	global_load_dwordx4 v[208:211], v245, s[14:15]
	s_add_u32 s14, s14, 0x10000
	s_addc_u32 s15, s15, 0
	global_load_dwordx4 v[216:219], v245, s[14:15]
	s_add_u32 s14, s14, 0x10000
	s_addc_u32 s15, s15, 0
	global_load_dwordx4 v[220:223], v245, s[14:15]
	s_add_u32 s14, s14, 0x10000
	s_addc_u32 s15, s15, 0
	global_load_dwordx4 v[224:227], v245, s[14:15]
	s_add_u32 s14, s14, 0x10000
	s_addc_u32 s15, s15, 0
	global_load_dwordx4 v[228:231], v245, s[14:15]
	s_add_u32 s14, s14, 0x10000
	s_addc_u32 s15, s15, 0
	global_load_dwordx4 v[232:235], v245, s[14:15]
	s_waitcnt vmcnt(15)
	v_mov_b64_e32 v[236:237], v[168:169]
	v_mov_b64_e32 v[238:239], v[170:171]
	global_load_dwordx4 v[168:171], v246, s[16:17]
	s_add_u32 s16, s16, 0x10000
	s_addc_u32 s17, s17, 0
	s_waitcnt vmcnt(15)
	v_pk_add_f32 v[238:239], v[238:239], v[174:175]
	v_pk_add_f32 v[236:237], v[236:237], v[172:173]
	global_load_dwordx4 v[172:175], v246, s[16:17]
	s_add_u32 s16, s16, 0x10000
	s_addc_u32 s17, s17, 0
	s_waitcnt vmcnt(15)
	v_pk_add_f32 v[238:239], v[238:239], v[178:179]
	v_pk_add_f32 v[236:237], v[236:237], v[176:177]
	global_load_dwordx4 v[176:179], v246, s[16:17]
	s_add_u32 s16, s16, 0x10000
	s_addc_u32 s17, s17, 0
	s_waitcnt vmcnt(15)
	v_pk_add_f32 v[238:239], v[238:239], v[182:183]
	v_pk_add_f32 v[236:237], v[236:237], v[180:181]
	global_load_dwordx4 v[180:183], v246, s[16:17]
	s_add_u32 s16, s16, 0x10000
	s_addc_u32 s17, s17, 0
	s_waitcnt vmcnt(15)
	v_pk_add_f32 v[238:239], v[238:239], v[186:187]
	v_pk_add_f32 v[236:237], v[236:237], v[184:185]
	global_load_dwordx4 v[184:187], v246, s[16:17]
	s_add_u32 s16, s16, 0x10000
	s_addc_u32 s17, s17, 0
	s_waitcnt vmcnt(15)
	v_pk_add_f32 v[238:239], v[238:239], v[190:191]
	v_pk_add_f32 v[236:237], v[236:237], v[188:189]
	global_load_dwordx4 v[188:191], v246, s[16:17]
	s_add_u32 s16, s16, 0x10000
	s_addc_u32 s17, s17, 0
	s_waitcnt vmcnt(15)
	v_pk_add_f32 v[238:239], v[238:239], v[194:195]
	v_pk_add_f32 v[236:237], v[236:237], v[192:193]
	global_load_dwordx4 v[192:195], v246, s[16:17]
	s_add_u32 s16, s16, 0x10000
	s_addc_u32 s17, s17, 0
	s_waitcnt vmcnt(15)
	v_pk_add_f32 v[238:239], v[238:239], v[198:199]
	v_pk_add_f32 v[236:237], v[236:237], v[196:197]
	global_load_dwordx4 v[196:199], v246, s[16:17]
	s_add_u32 s16, s16, 0x10000
	s_addc_u32 s17, s17, 0
	s_waitcnt vmcnt(15)
	v_pk_add_f32 v[238:239], v[238:239], v[202:203]
	v_pk_add_f32 v[236:237], v[236:237], v[200:201]
	global_load_dwordx4 v[200:203], v246, s[16:17]
	s_add_u32 s16, s16, 0x10000
	s_addc_u32 s17, s17, 0
	s_waitcnt vmcnt(15)
	v_pk_add_f32 v[238:239], v[238:239], v[206:207]
	v_pk_add_f32 v[236:237], v[236:237], v[204:205]
	global_load_dwordx4 v[204:207], v246, s[16:17]
	s_add_u32 s16, s16, 0x10000
	s_addc_u32 s17, s17, 0
	s_waitcnt vmcnt(15)
	v_pk_add_f32 v[238:239], v[238:239], v[210:211]
	v_pk_add_f32 v[236:237], v[236:237], v[208:209]
	global_load_dwordx4 v[208:211], v246, s[16:17]
	s_add_u32 s16, s16, 0x10000
	s_addc_u32 s17, s17, 0
	s_waitcnt vmcnt(15)
	v_pk_add_f32 v[238:239], v[238:239], v[218:219]
	v_pk_add_f32 v[236:237], v[236:237], v[216:217]
	global_load_dwordx4 v[216:219], v246, s[16:17]
	s_add_u32 s16, s16, 0x10000
	s_addc_u32 s17, s17, 0
	s_waitcnt vmcnt(15)
	v_pk_add_f32 v[238:239], v[238:239], v[222:223]
	v_pk_add_f32 v[236:237], v[236:237], v[220:221]
	global_load_dwordx4 v[220:223], v246, s[16:17]
	s_add_u32 s16, s16, 0x10000
	s_addc_u32 s17, s17, 0
	s_waitcnt vmcnt(15)
	v_pk_add_f32 v[238:239], v[238:239], v[226:227]
	v_pk_add_f32 v[236:237], v[236:237], v[224:225]
	global_load_dwordx4 v[224:227], v246, s[16:17]
	s_add_u32 s16, s16, 0x10000
	s_addc_u32 s17, s17, 0
	s_waitcnt vmcnt(15)
	v_pk_add_f32 v[238:239], v[238:239], v[230:231]
	v_pk_add_f32 v[236:237], v[236:237], v[228:229]
	global_load_dwordx4 v[228:231], v246, s[16:17]
	s_add_u32 s16, s16, 0x10000
	s_addc_u32 s17, s17, 0
	s_waitcnt vmcnt(15)
	v_pk_add_f32 v[238:239], v[238:239], v[234:235]
	v_pk_add_f32 v[236:237], v[236:237], v[232:233]
	global_load_dwordx4 v[232:235], v246, s[16:17]
	ds_write_b128 v247, v[140:143]
	ds_write_b128 v247, v[144:147] offset:8192
	ds_write_b128 v247, v[148:151] offset:16384
	ds_write_b128 v247, v[152:155] offset:24576
	ds_write_b128 v247, v[156:159] offset:32768
	ds_write_b128 v247, v[160:163] offset:40960
	ds_write_b128 v247, v[164:167] offset:49152
	ds_write_b128 v245, v[236:239]
	s_waitcnt vmcnt(15)
	v_mov_b64_e32 v[240:241], v[168:169]
	v_mov_b64_e32 v[242:243], v[170:171]
	s_waitcnt vmcnt(14)
	v_pk_add_f32 v[242:243], v[242:243], v[174:175]
	v_pk_add_f32 v[240:241], v[240:241], v[172:173]
	s_waitcnt vmcnt(13)
	v_pk_add_f32 v[242:243], v[242:243], v[178:179]
	v_pk_add_f32 v[240:241], v[240:241], v[176:177]
	s_waitcnt vmcnt(12)
	v_pk_add_f32 v[242:243], v[242:243], v[182:183]
	v_pk_add_f32 v[240:241], v[240:241], v[180:181]
	s_waitcnt vmcnt(11)
	v_pk_add_f32 v[242:243], v[242:243], v[186:187]
	v_pk_add_f32 v[240:241], v[240:241], v[184:185]
	s_waitcnt vmcnt(10)
	v_pk_add_f32 v[242:243], v[242:243], v[190:191]
	v_pk_add_f32 v[240:241], v[240:241], v[188:189]
	s_waitcnt vmcnt(9)
	v_pk_add_f32 v[242:243], v[242:243], v[194:195]
	v_pk_add_f32 v[240:241], v[240:241], v[192:193]
	s_waitcnt vmcnt(8)
	v_pk_add_f32 v[242:243], v[242:243], v[198:199]
	v_pk_add_f32 v[240:241], v[240:241], v[196:197]
	s_waitcnt vmcnt(7)
	v_pk_add_f32 v[242:243], v[242:243], v[202:203]
	v_pk_add_f32 v[240:241], v[240:241], v[200:201]
	s_waitcnt vmcnt(6)
	v_pk_add_f32 v[242:243], v[242:243], v[206:207]
	v_pk_add_f32 v[240:241], v[240:241], v[204:205]
	s_waitcnt vmcnt(5)
	v_pk_add_f32 v[242:243], v[242:243], v[210:211]
	v_pk_add_f32 v[240:241], v[240:241], v[208:209]
	s_waitcnt vmcnt(4)
	v_pk_add_f32 v[242:243], v[242:243], v[218:219]
	v_pk_add_f32 v[240:241], v[240:241], v[216:217]
	s_waitcnt vmcnt(3)
	v_pk_add_f32 v[242:243], v[242:243], v[222:223]
	v_pk_add_f32 v[240:241], v[240:241], v[220:221]
	s_waitcnt vmcnt(2)
	v_pk_add_f32 v[242:243], v[242:243], v[226:227]
	v_pk_add_f32 v[240:241], v[240:241], v[224:225]
	s_waitcnt vmcnt(1)
	v_pk_add_f32 v[242:243], v[242:243], v[230:231]
	v_pk_add_f32 v[240:241], v[240:241], v[228:229]
	s_waitcnt vmcnt(0)
	v_pk_add_f32 v[242:243], v[242:243], v[234:235]
	v_pk_add_f32 v[240:241], v[240:241], v[232:233]
	ds_write_b128 v246, v[240:243]
.LBB0_130:
	v_ashrrev_i32_e32 v0, 6, v12
	v_add_u32_e32 v74, s85, v0
	s_movk_i32 s0, 0x800
	v_cmp_gt_i32_e32 vcc, s0, v74
	v_mbcnt_lo_u32_b32 v215, -1, 0
	s_waitcnt lgkmcnt(0)
	s_barrier
	s_and_saveexec_b64 s[8:9], vcc
	s_cbranch_execz .LBB0_138
	v_mbcnt_hi_u32_b32 v3, -1, v215
	v_and_b32_e32 v5, 64, v3
	v_xor_b32_e32 v4, 16, v3
	v_add_u32_e32 v5, 64, v5
	v_cmp_lt_i32_e32 vcc, v4, v5
	v_and_b32_e32 v1, 63, v12
	v_mov_b32_e32 v25, 0
	v_cndmask_b32_e32 v4, v3, v4, vcc
	v_lshlrev_b32_e32 v75, 2, v4
	v_xor_b32_e32 v4, 32, v3
	v_cmp_lt_i32_e32 vcc, v4, v5
	v_lshlrev_b32_e32 v24, 4, v1
	s_add_i32 s0, 0, 0x1c000
	v_cndmask_b32_e32 v3, v3, v4, vcc
	v_lshlrev_b32_e32 v4, 3, v1
	v_mov_b32_e32 v5, v25
	v_add_u32_e32 v77, s0, v24
	v_lshl_add_u64 v[4:5], s[4:5], 0, v[4:5]
	s_mov_b64 s[0:1], 0xe000000
	v_lshl_add_u64 v[28:29], v[4:5], 0, s[0:1]
	s_add_i32 s0, 0, 0x10000
	v_add_u32_e32 v78, s0, v24
	v_readlane_b32 s0, v251, 0
	v_lshlrev_b32_e32 v2, 2, v1
	v_lshlrev_b32_e32 v0, 2, v0
	v_readlane_b32 s1, v251, 1
	v_lshl_add_u64 v[26:27], s[6:7], 0, v[24:25]
	v_lshlrev_b32_e32 v76, 2, v3
	v_cmp_gt_u32_e64 s[6:7], 16, v1
	v_add_u32_e32 v79, 0, v24
	v_lshl_add_u32 v80, s2, 5, v0
	s_lshl_b32 s0, s0, 5
	s_mov_b64 s[10:11], 0
	s_movk_i32 s1, 0x1000
	v_mov_b32_e32 v81, 0x358637bd
	s_mov_b32 s3, 0x800000
	s_mov_b32 s16, 0x6000000
	s_brev_b32 s17, 64
	s_brev_b32 s18, 32
	s_brev_b32 s19, 16
	s_mov_b32 s20, 0xa000000
	v_lshlrev_b32_e32 v24, 1, v2
	s_movk_i32 s21, 0x7ff
	v_mov_b32_e32 v84, v25
	v_mov_b32_e32 v85, v25
	s_branch .LBB0_133
